# v43 + attention QK: sub-head-0 Q fragments and accumulator init prefetched in front of the tile barrier, K-only reads after it (4 K buffers), sub-head-1 Q fragments requested 4 steps ahead
# baseline (speedup 1.0000x reference)
; #define LAS __attribute__((address_space(3)))
; __device__ __forceinline__ unsigned cvtpk(float lo, float hi) { return pg8::cvt_pk_bf16(lo, hi); }
; __device__ __forceinline__ float bflo(unsigned u) { return __uint_as_float(u << 16); }
; __device__ __forceinline__ float bfhi(unsigned u) { return __uint_as_float(u & 0xffff0000u); }
; __device__ __forceinline__ void attn_phase(LAS unsigned char* lds, const bf16_t* proj, bf16_t* oa, const float* lamp, const float* subg, const float* relb, const float* qg, int wg, int tid) {
;     ...
;         const int qb = (ui == 0) ? sx : (ui == 1) ? 15 - sx : (ui == 2) ? 16 + sx : 31 - sx;
;         const int q0 = qb * 128, qw0 = q0 + wave * 16, nkt = (q0 + 128) / 32;
;         LAS bf16_t* Qw = Qs + wave * (2 * 16 * KP);
; #pragma unroll
;         for (int s = 0; s < 2; ++s) { u32x4 qc[4]; float ss = 0.f;
; #pragma unroll
;             for (int ks = 0; ks < 4; ++ks) { qc[ks] = *(const u32x4*)(proj + (rb + qw0 + fr) * DIFF_IN + (2 * h + s) * 128 + 32 * ks + 8 * fq);
; #pragma unroll
;                 for (int e = 0; e < 4; ++e) { const float a = bflo(qc[ks][e]), c = bfhi(qc[ks][e]); ss += a * a + c * c; } }
;             ss += __shfl_xor(ss, 16); ss += __shfl_xor(ss, 32);
;             const float rs = (1.0f / sqrtf(ss * (1.f / 128.f) + EPS)) * QSCALE;
; #pragma unroll
;             for (int ks = 0; ks < 4; ++ks) { const f32x4 g0 = *(const f32x4*)(qg + 32 * ks + 8 * fq), g1 = *(const f32x4*)(qg + 32 * ks + 8 * fq + 4);
;                 u32x4 o; o.x = cvtpk(bflo(qc[ks].x) * rs * g0[0], bfhi(qc[ks].x) * rs * g0[1]); o.y = cvtpk(bflo(qc[ks].y) * rs * g0[2], bfhi(qc[ks].y) * rs * g0[3]);
;                 o.z = cvtpk(bflo(qc[ks].z) * rs * g1[0], bfhi(qc[ks].z) * rs * g1[1]); o.w = cvtpk(bflo(qc[ks].w) * rs * g1[2], bfhi(qc[ks].w) * rs * g1[3]);
;                 *(LAS u32x4*)(Qw + (s * 16 + fr) * KP + 32 * ks + 8 * fq) = o; } }
.LBB0_593:
	s_lshl_b32 s0, s20, 7
	s_add_i32 s40, s0, s6
	s_ashr_i32 s41, s40, 31
	v_lshl_add_u64 v[18:19], v[168:169], 0, s[40:41]
	v_mad_u64_u32 v[58:59], s[20:21], v18, s28, v[200:201]
	v_mov_b32_e32 v0, v59
	v_mad_u64_u32 v[18:19], s[20:21], v19, s28, v[0:1]
	v_mov_b32_e32 v59, v18
	global_load_dwordx4 v[38:41], v[58:59], off offset:192
	global_load_dwordx4 v[42:45], v[58:59], off
	global_load_dwordx4 v[46:49], v[58:59], off offset:64
	global_load_dwordx4 v[84:87], v[58:59], off offset:128
	global_load_dwordx4 v[18:21], v[170:171], off offset:16
	global_load_dwordx4 v[22:25], v[170:171], off
	global_load_dwordx4 v[26:29], v[170:171], off offset:144
	global_load_dwordx4 v[30:33], v[170:171], off offset:128
	global_load_dwordx4 v[34:37], v[170:171], off offset:256
	s_add_i32 s20, s0, 0x80
	s_mov_b32 s33, 1
	s_lshr_b32 s34, s20, 5
	s_or_b32 s35, s40, 15
	s_sub_i32 s36, s40, 31
	s_mov_b32 s37, 0
	v_mov_b64_e32 v[210:211], v[208:209]
	v_mov_b64_e32 v[212:213], v[206:207]
	v_mov_b64_e32 v[214:215], v[204:205]
	v_mov_b64_e32 v[216:217], v[202:203]
	s_waitcnt vmcnt(8)
	v_and_b32_e32 v57, 0xffff0000, v39
	s_waitcnt vmcnt(7)
	v_lshlrev_b32_e32 v76, 16, v45
	v_and_b32_e32 v77, 0xffff0000, v45
	v_lshlrev_b32_e32 v80, 16, v43
	v_and_b32_e32 v81, 0xffff0000, v43
	v_lshlrev_b32_e32 v82, 16, v42
	v_and_b32_e32 v83, 0xffff0000, v42
	v_lshlrev_b32_e32 v78, 16, v44
	v_and_b32_e32 v79, 0xffff0000, v44
	s_waitcnt vmcnt(6)
	v_lshlrev_b32_e32 v64, 16, v49
	v_and_b32_e32 v65, 0xffff0000, v49
	v_lshlrev_b32_e32 v68, 16, v48
	v_and_b32_e32 v69, 0xffff0000, v48
	v_lshlrev_b32_e32 v72, 16, v47
	v_and_b32_e32 v73, 0xffff0000, v47
	v_lshlrev_b32_e32 v74, 16, v46
	v_and_b32_e32 v75, 0xffff0000, v46
	v_pk_mul_f32 v[42:43], v[76:77], v[76:77]
	v_pk_mul_f32 v[46:47], v[80:81], v[80:81]
	v_pk_mul_f32 v[48:49], v[82:83], v[82:83]
	v_pk_mul_f32 v[44:45], v[78:79], v[78:79]
	v_add_f32_e32 v0, v42, v43
	v_add_f32_e32 v42, v46, v47
	v_add_f32_e32 v43, v48, v49
	v_add_f32_e32 v44, v44, v45
	v_add_f32_e32 v42, v43, v42
	v_pk_mul_f32 v[90:91], v[74:75], v[74:75]
	v_add_f32_e32 v42, v44, v42
	v_pk_mul_f32 v[88:89], v[72:73], v[72:73]
	v_add_f32_e32 v45, v90, v91
	v_add_f32_e32 v0, v0, v42
	s_waitcnt vmcnt(5)
	v_lshlrev_b32_e32 v60, 16, v87
	v_and_b32_e32 v61, 0xffff0000, v87
	v_lshlrev_b32_e32 v62, 16, v86
	v_and_b32_e32 v63, 0xffff0000, v86
	v_pk_mul_f32 v[86:87], v[68:69], v[68:69]
	v_add_f32_e32 v46, v88, v89
	v_add_f32_e32 v0, v45, v0
	v_lshlrev_b32_e32 v66, 16, v85
	v_and_b32_e32 v67, 0xffff0000, v85
	v_lshlrev_b32_e32 v70, 16, v84
	v_and_b32_e32 v71, 0xffff0000, v84
	v_pk_mul_f32 v[84:85], v[64:65], v[64:65]
	v_add_f32_e32 v47, v86, v87
	v_add_f32_e32 v0, v46, v0
	v_pk_mul_f32 v[98:99], v[70:71], v[70:71]
	v_add_f32_e32 v48, v84, v85
	v_add_f32_e32 v0, v47, v0
	v_pk_mul_f32 v[96:97], v[66:67], v[66:67]
	v_add_f32_e32 v49, v98, v99
	v_add_f32_e32 v0, v48, v0
	v_pk_mul_f32 v[94:95], v[62:63], v[62:63]
	v_add_f32_e32 v84, v96, v97
	v_add_f32_e32 v0, v49, v0
	v_and_b32_e32 v56, 0xffff0000, v38
	v_pk_mul_f32 v[92:93], v[60:61], v[60:61]
	v_add_f32_e32 v85, v94, v95
	v_add_f32_e32 v0, v84, v0
	v_lshlrev_b32_e32 v55, 16, v39
	v_lshlrev_b32_e32 v54, 16, v38
	v_pk_mul_f32 v[38:39], v[56:57], v[56:57]
	v_add_f32_e32 v86, v92, v93
	v_add_f32_e32 v0, v85, v0
	v_and_b32_e32 v53, 0xffff0000, v41
	v_and_b32_e32 v52, 0xffff0000, v40
	v_pk_fma_f32 v[38:39], v[54:55], v[54:55], v[38:39]
	v_add_f32_e32 v0, v86, v0
	v_lshlrev_b32_e32 v51, 16, v41
	v_lshlrev_b32_e32 v50, 16, v40
	v_pk_mul_f32 v[40:41], v[52:53], v[52:53]
	v_add_f32_e32 v0, v38, v0
	v_pk_fma_f32 v[40:41], v[50:51], v[50:51], v[40:41]
	v_add_f32_e32 v0, v39, v0
	v_add_f32_e32 v0, v40, v0
	v_add_f32_e32 v0, v41, v0
	ds_bpermute_b32 v42, v232, v0
	global_load_dwordx4 v[38:41], v[170:171], off offset:272
	s_waitcnt lgkmcnt(0)
	v_add_f32_e32 v0, v0, v42
	ds_bpermute_b32 v92, v233, v0
	global_load_dwordx4 v[42:45], v[170:171], off offset:400
	global_load_dwordx4 v[46:49], v[170:171], off offset:384
	global_load_dwordx4 v[84:87], v[58:59], off offset:384
	global_load_dwordx4 v[88:91], v[58:59], off offset:448
	s_waitcnt lgkmcnt(0)
	v_add_f32_e32 v0, v0, v92
	v_fmamk_f32 v0, v0, 0x3c000000, v189
	v_mul_f32_e32 v92, 0x4f800000, v0
	v_cmp_gt_f32_e32 vcc, s22, v0
	s_waitcnt vmcnt(1)
; #define LAS __attribute__((address_space(3)))
; __device__ __forceinline__ unsigned cvtpk(float lo, float hi) { return pg8::cvt_pk_bf16(lo, hi); }
; __device__ __forceinline__ float bflo(unsigned u) { return __uint_as_float(u << 16); }
; __device__ __forceinline__ float bfhi(unsigned u) { return __uint_as_float(u & 0xffff0000u); }
; __device__ __forceinline__ void attn_phase(LAS unsigned char* lds, const bf16_t* proj, bf16_t* oa, const float* lamp, const float* subg, const float* relb, const float* qg, int wg, int tid) {
;     ...
;         for (int s = 0; s < 2; ++s) { u32x4 qc[4]; float ss = 0.f;
; #pragma unroll
;             for (int ks = 0; ks < 4; ++ks) { qc[ks] = *(const u32x4*)(proj + (rb + qw0 + fr) * DIFF_IN + (2 * h + s) * 128 + 32 * ks + 8 * fq);
; #pragma unroll
;                 for (int e = 0; e < 4; ++e) { const float a = bflo(qc[ks][e]), c = bfhi(qc[ks][e]); ss += a * a + c * c; } }
;             ss += __shfl_xor(ss, 16); ss += __shfl_xor(ss, 32);
;             const float rs = (1.0f / sqrtf(ss * (1.f / 128.f) + EPS)) * QSCALE;
; #pragma unroll
;             for (int ks = 0; ks < 4; ++ks) { const f32x4 g0 = *(const f32x4*)(qg + 32 * ks + 8 * fq), g1 = *(const f32x4*)(qg + 32 * ks + 8 * fq + 4);
;                 u32x4 o; o.x = cvtpk(bflo(qc[ks].x) * rs * g0[0], bfhi(qc[ks].x) * rs * g0[1]); o.y = cvtpk(bflo(qc[ks].y) * rs * g0[2], bfhi(qc[ks].y) * rs * g0[3]);
;                 o.z = cvtpk(bflo(qc[ks].z) * rs * g1[0], bfhi(qc[ks].z) * rs * g1[1]); o.w = cvtpk(bflo(qc[ks].w) * rs * g1[2], bfhi(qc[ks].w) * rs * g1[3]);
;                 *(LAS u32x4*)(Qw + (s * 16 + fr) * KP + 32 * ks + 8 * fq) = o; } }
	v_lshlrev_b32_e32 v116, 16, v84
	v_cndmask_b32_e32 v0, v0, v92, vcc
	v_sqrt_f32_e32 v96, v0
	global_load_dwordx4 v[92:95], v[58:59], off offset:256
	v_and_b32_e32 v117, 0xffff0000, v84
	v_lshlrev_b32_e32 v112, 16, v85
	v_add_u32_e32 v97, -1, v96
	v_add_u32_e32 v98, 1, v96
	v_fma_f32 v99, -v97, v96, v0
	v_fma_f32 v100, -v98, v96, v0
	v_cmp_ge_f32_e64 s[0:1], 0, v99
	v_and_b32_e32 v113, 0xffff0000, v85
	v_pk_mul_f32 v[84:85], v[116:117], v[116:117]
	v_cndmask_b32_e64 v96, v96, v97, s[0:1]
	v_cmp_lt_f32_e64 s[0:1], 0, v100
	v_lshlrev_b32_e32 v110, 16, v86
	v_and_b32_e32 v111, 0xffff0000, v86
	v_cndmask_b32_e64 v96, v96, v98, s[0:1]
	v_mul_f32_e32 v97, 0x37800000, v96
	v_cndmask_b32_e32 v96, v96, v97, vcc
	v_cmp_class_f32_e32 vcc, v0, v191
	v_pk_mul_f32 v[114:115], v[112:113], v[112:113]
	v_lshlrev_b32_e32 v106, 16, v87
	v_cndmask_b32_e32 v0, v96, v0, vcc
	global_load_dwordx4 v[96:99], v[58:59], off offset:320
	v_div_scale_f32 v100, s[0:1], v0, v0, 1.0
	v_rcp_f32_e32 v101, v100
	v_div_scale_f32 v58, vcc, 1.0, v0, 1.0
	v_and_b32_e32 v107, 0xffff0000, v87
	v_fma_f32 v59, -v100, v101, 1.0
	v_fmac_f32_e32 v101, v59, v101
	v_mul_f32_e32 v59, v58, v101
	v_fma_f32 v102, -v100, v59, v58
	v_fmac_f32_e32 v59, v102, v101
	v_fma_f32 v58, -v100, v59, v58
	v_div_fmas_f32 v58, v58, v101, v59
	v_div_fixup_f32 v0, v58, v0, 1.0
	v_mul_f32_e32 v0, 0x3e0293ee, v0
	v_pk_mul_f32 v[58:59], v[0:1], v[82:83] op_sel_hi:[0,1]
	v_pk_mul_f32 v[78:79], v[0:1], v[78:79] op_sel_hi:[0,1]
	v_pk_mul_f32 v[82:83], v[0:1], v[76:77] op_sel_hi:[0,1]
	v_pk_mul_f32 v[58:59], v[22:23], v[58:59]
	v_pk_mul_f32 v[78:79], v[18:19], v[78:79]
	v_cvt_pk_bf16_f32 v76, v58, v59
	v_pk_mul_f32 v[58:59], v[20:21], v[82:83]
	v_cvt_pk_bf16_f32 v78, v78, v79
	v_cvt_pk_bf16_f32 v79, v58, v59
	v_pk_mul_f32 v[58:59], v[0:1], v[74:75] op_sel_hi:[0,1]
	v_pk_mul_f32 v[58:59], v[30:31], v[58:59]
	v_pk_mul_f32 v[80:81], v[0:1], v[80:81] op_sel_hi:[0,1]
	v_cvt_pk_bf16_f32 v74, v58, v59
	v_pk_mul_f32 v[58:59], v[0:1], v[72:73] op_sel_hi:[0,1]
	v_pk_mul_f32 v[58:59], v[32:33], v[58:59]
	v_pk_mul_f32 v[80:81], v[24:25], v[80:81]
	v_cvt_pk_bf16_f32 v75, v58, v59
	v_pk_mul_f32 v[58:59], v[0:1], v[68:69] op_sel_hi:[0,1]
	v_cvt_pk_bf16_f32 v77, v80, v81
	v_pk_mul_f32 v[58:59], v[26:27], v[58:59]
	ds_write_b128 v248, v[76:79]
	v_cvt_pk_bf16_f32 v76, v58, v59
	v_pk_mul_f32 v[58:59], v[0:1], v[64:65] op_sel_hi:[0,1]
	v_pk_mul_f32 v[58:59], v[28:29], v[58:59]
	v_pk_mul_f32 v[86:87], v[110:111], v[110:111]
	v_cvt_pk_bf16_f32 v77, v58, v59
	v_pk_mul_f32 v[58:59], v[0:1], v[70:71] op_sel_hi:[0,1]
	v_pk_mul_f32 v[58:59], v[34:35], v[58:59]
	ds_write_b128 v248, v[74:77] offset:64
	v_cvt_pk_bf16_f32 v64, v58, v59
	v_pk_mul_f32 v[58:59], v[0:1], v[66:67] op_sel_hi:[0,1]
	v_pk_mul_f32 v[58:59], v[36:37], v[58:59]
	v_pk_mul_f32 v[108:109], v[106:107], v[106:107]
	v_cvt_pk_bf16_f32 v65, v58, v59
	v_pk_mul_f32 v[58:59], v[0:1], v[62:63] op_sel_hi:[0,1]
	v_pk_mul_f32 v[58:59], v[38:39], v[58:59]
	s_waitcnt vmcnt(2)
	v_and_b32_e32 v63, 0xffff0000, v89
	v_cvt_pk_bf16_f32 v66, v58, v59
	v_pk_mul_f32 v[58:59], v[0:1], v[60:61] op_sel_hi:[0,1]
	v_pk_mul_f32 v[58:59], v[40:41], v[58:59]
	v_and_b32_e32 v62, 0xffff0000, v88
	v_cvt_pk_bf16_f32 v67, v58, v59
	v_mov_b32_e32 v58, v54
	v_mov_b32_e32 v59, v56
	v_pk_mul_f32 v[58:59], v[0:1], v[58:59] op_sel_hi:[0,1]
	v_pk_mul_f32 v[58:59], v[46:47], v[58:59]
	s_waitcnt vmcnt(1)
	v_lshlrev_b32_e32 v78, 16, v95
	v_cvt_pk_bf16_f32 v54, v58, v59
	v_lshlrev_b32_e32 v59, 16, v89
	v_lshlrev_b32_e32 v58, 16, v88
	v_and_b32_e32 v79, 0xffff0000, v95
	v_lshlrev_b32_e32 v82, 16, v93
	v_and_b32_e32 v83, 0xffff0000, v93
	v_lshlrev_b32_e32 v88, 16, v92
	v_and_b32_e32 v89, 0xffff0000, v92
	v_pk_mul_f32 v[70:71], v[78:79], v[78:79]
	v_lshlrev_b32_e32 v80, 16, v94
	v_and_b32_e32 v81, 0xffff0000, v94
	v_pk_mul_f32 v[74:75], v[82:83], v[82:83]
	v_pk_mul_f32 v[76:77], v[88:89], v[88:89]
	v_pk_mul_f32 v[72:73], v[80:81], v[80:81]
	v_add_f32_e32 v56, v70, v71
	v_add_f32_e32 v70, v74, v75
	v_add_f32_e32 v71, v76, v77
	s_waitcnt vmcnt(0)
	v_lshlrev_b32_e32 v104, 16, v96
	v_and_b32_e32 v105, 0xffff0000, v96
	v_add_f32_e32 v70, v71, v70
	v_add_f32_e32 v71, v72, v73
	v_lshlrev_b32_e32 v100, 16, v97
	v_and_b32_e32 v101, 0xffff0000, v97
	v_pk_mul_f32 v[96:97], v[104:105], v[104:105]
	v_add_f32_e32 v70, v71, v70
	v_pk_mul_f32 v[60:61], v[62:63], v[62:63]
	v_lshlrev_b32_e32 v94, 16, v98
	v_and_b32_e32 v95, 0xffff0000, v98
	v_pk_mul_f32 v[102:103], v[100:101], v[100:101]
	v_add_f32_e32 v56, v56, v70
	v_add_f32_e32 v70, v96, v97
	ds_write_b128 v248, v[64:67] offset:128
	v_pk_fma_f32 v[66:67], v[58:59], v[58:59], v[60:61]
	v_lshlrev_b32_e32 v61, 16, v91
	v_lshlrev_b32_e32 v60, 16, v90
	v_and_b32_e32 v65, 0xffff0000, v91
	v_and_b32_e32 v64, 0xffff0000, v90
	v_lshlrev_b32_e32 v90, 16, v99
	v_and_b32_e32 v91, 0xffff0000, v99
	v_pk_mul_f32 v[98:99], v[94:95], v[94:95]
	v_add_f32_e32 v56, v70, v56
	v_add_f32_e32 v70, v102, v103
	v_pk_mul_f32 v[92:93], v[90:91], v[90:91]
	v_add_f32_e32 v56, v70, v56
	v_add_f32_e32 v70, v98, v99
	v_add_f32_e32 v56, v70, v56
	v_add_f32_e32 v70, v92, v93
	v_add_f32_e32 v56, v70, v56
	v_add_f32_e32 v70, v84, v85
	v_add_f32_e32 v56, v70, v56
	v_add_f32_e32 v70, v114, v115
	v_add_f32_e32 v56, v70, v56
	v_add_f32_e32 v70, v86, v87
	v_add_f32_e32 v56, v70, v56
	v_add_f32_e32 v70, v108, v109
	v_add_f32_e32 v56, v70, v56
	v_pk_mul_f32 v[68:69], v[64:65], v[64:65]
	v_add_f32_e32 v56, v66, v56
	v_pk_fma_f32 v[68:69], v[60:61], v[60:61], v[68:69]
	v_add_f32_e32 v56, v67, v56
	v_add_f32_e32 v56, v68, v56
	v_add_f32_e32 v66, v69, v56
	ds_bpermute_b32 v67, v232, v66
	v_mov_b32_e32 v56, v55
	v_pk_mul_f32 v[56:57], v[0:1], v[56:57] op_sel_hi:[0,1]
	v_pk_mul_f32 v[56:57], v[48:49], v[56:57]
	s_waitcnt lgkmcnt(0)
; #define LAS __attribute__((address_space(3)))
; __device__ __forceinline__ unsigned cvtpk(float lo, float hi) { return pg8::cvt_pk_bf16(lo, hi); }
; __device__ __forceinline__ float bflo(unsigned u) { return __uint_as_float(u << 16); }
; __device__ __forceinline__ float bfhi(unsigned u) { return __uint_as_float(u & 0xffff0000u); }
; __device__ __forceinline__ void attn_phase(LAS unsigned char* lds, const bf16_t* proj, bf16_t* oa, const float* lamp, const float* subg, const float* relb, const float* qg, int wg, int tid) {
;     ...
;         for (int s = 0; s < 2; ++s) { u32x4 qc[4]; float ss = 0.f;
; #pragma unroll
;             for (int ks = 0; ks < 4; ++ks) { qc[ks] = *(const u32x4*)(proj + (rb + qw0 + fr) * DIFF_IN + (2 * h + s) * 128 + 32 * ks + 8 * fq);
; #pragma unroll
;                 for (int e = 0; e < 4; ++e) { const float a = bflo(qc[ks][e]), c = bfhi(qc[ks][e]); ss += a * a + c * c; } }
;             ss += __shfl_xor(ss, 16); ss += __shfl_xor(ss, 32);
;             const float rs = (1.0f / sqrtf(ss * (1.f / 128.f) + EPS)) * QSCALE;
; #pragma unroll
;             for (int ks = 0; ks < 4; ++ks) { const f32x4 g0 = *(const f32x4*)(qg + 32 * ks + 8 * fq), g1 = *(const f32x4*)(qg + 32 * ks + 8 * fq + 4);
;                 u32x4 o; o.x = cvtpk(bflo(qc[ks].x) * rs * g0[0], bfhi(qc[ks].x) * rs * g0[1]); o.y = cvtpk(bflo(qc[ks].y) * rs * g0[2], bfhi(qc[ks].y) * rs * g0[3]);
;                 o.z = cvtpk(bflo(qc[ks].z) * rs * g1[0], bfhi(qc[ks].z) * rs * g1[1]); o.w = cvtpk(bflo(qc[ks].w) * rs * g1[2], bfhi(qc[ks].w) * rs * g1[3]);
;                 *(LAS u32x4*)(Qw + (s * 16 + fr) * KP + 32 * ks + 8 * fq) = o; } }
; #pragma unroll
;         for (int i = 0; i < 2; ++i) { const int id = tid + 512 * i, s = id >> 9, row = (id >> 4) & 31, ch = id & 15;
;             *(LAS u32x4*)(Kb + (s * 32 + row) * KP + ch * 8) = *(const u32x4*)(ksrc + (size_t)row * DIFF_IN + s * 128 + ch * 8); }
; #pragma unroll
;         for (int i = 0; i < 2; ++i) { const int id = tid + 512 * i, row = id >> 5, ch = id & 31;
;             *(LAS u32x4*)(Vb + row * VP + ch * 8) = *(const u32x4*)(vsrc + (size_t)row * DIFF_IN + ch * 8); }
	v_add_f32_e32 v66, v66, v67
	ds_bpermute_b32 v67, v233, v66
	v_cvt_pk_bf16_f32 v55, v56, v57
	v_mov_b32_e32 v56, v50
	v_mov_b32_e32 v57, v52
	v_pk_mul_f32 v[56:57], v[0:1], v[56:57] op_sel_hi:[0,1]
	s_waitcnt lgkmcnt(0)
	v_add_f32_e32 v50, v66, v67
	v_fmamk_f32 v50, v50, 0x3c000000, v189
	v_mul_f32_e32 v52, 0x4f800000, v50
	v_cmp_gt_f32_e32 vcc, s22, v50
	v_pk_mul_f32 v[56:57], v[42:43], v[56:57]
	s_nop 0
	v_cndmask_b32_e32 v50, v50, v52, vcc
	v_sqrt_f32_e32 v66, v50
	v_mov_b32_e32 v52, v51
	v_pk_mul_f32 v[84:85], v[0:1], v[52:53] op_sel_hi:[0,1]
	v_pk_mul_f32 v[84:85], v[44:45], v[84:85]
	v_add_u32_e32 v0, -1, v66
	v_fma_f32 v51, -v0, v66, v50
	v_cmp_ge_f32_e64 s[0:1], 0, v51
	v_add_u32_e32 v51, 1, v66
	v_fma_f32 v52, -v51, v66, v50
	v_cndmask_b32_e64 v0, v66, v0, s[0:1]
	v_cmp_lt_f32_e64 s[0:1], 0, v52
	v_cvt_pk_bf16_f32 v56, v56, v57
	v_cvt_pk_bf16_f32 v57, v84, v85
	v_cndmask_b32_e64 v0, v0, v51, s[0:1]
	v_mul_f32_e32 v51, 0x37800000, v0
	v_cndmask_b32_e32 v0, v0, v51, vcc
	v_cmp_class_f32_e32 vcc, v50, v191
	s_nop 1
	v_cndmask_b32_e32 v0, v0, v50, vcc
	global_load_dwordx4 v[50:53], v[178:179], off
	global_load_dwordx4 v[66:69], v[180:181], off
	global_load_dwordx4 v[70:73], v[182:183], off
	global_load_dwordx4 v[74:77], v[184:185], off
	v_div_scale_f32 v86, s[0:1], v0, v0, 1.0
	v_rcp_f32_e32 v87, v86
	ds_write_b128 v248, v[54:57] offset:192
	v_fma_f32 v54, -v86, v87, 1.0
	v_fmac_f32_e32 v87, v54, v87
	v_div_scale_f32 v54, vcc, 1.0, v0, 1.0
	v_mul_f32_e32 v55, v54, v87
	v_fma_f32 v56, -v86, v55, v54
	v_fmac_f32_e32 v55, v56, v87
	v_fma_f32 v54, -v86, v55, v54
	v_div_fmas_f32 v54, v54, v87, v55
	v_div_fixup_f32 v0, v54, v0, 1.0
	v_mul_f32_e32 v0, 0x3e0293ee, v0
	v_pk_mul_f32 v[54:55], v[0:1], v[88:89] op_sel_hi:[0,1]
	v_pk_mul_f32 v[22:23], v[22:23], v[54:55]
	v_pk_mul_f32 v[54:55], v[0:1], v[82:83] op_sel_hi:[0,1]
	v_pk_mul_f32 v[24:25], v[24:25], v[54:55]
	v_cvt_pk_bf16_f32 v22, v22, v23
	v_cvt_pk_bf16_f32 v23, v24, v25
	v_pk_mul_f32 v[24:25], v[0:1], v[80:81] op_sel_hi:[0,1]
	v_pk_mul_f32 v[18:19], v[18:19], v[24:25]
	s_nop 0
	v_cvt_pk_bf16_f32 v24, v18, v19
	v_pk_mul_f32 v[18:19], v[0:1], v[78:79] op_sel_hi:[0,1]
	v_pk_mul_f32 v[18:19], v[20:21], v[18:19]
	v_pk_mul_f32 v[20:21], v[0:1], v[100:101] op_sel_hi:[0,1]
	v_cvt_pk_bf16_f32 v25, v18, v19
	v_pk_mul_f32 v[18:19], v[0:1], v[104:105] op_sel_hi:[0,1]
	v_pk_mul_f32 v[18:19], v[30:31], v[18:19]
	v_pk_mul_f32 v[20:21], v[32:33], v[20:21]
	ds_write_b128 v248, v[22:25] offset:4608
	v_cvt_pk_bf16_f32 v18, v18, v19
	v_cvt_pk_bf16_f32 v19, v20, v21
	v_pk_mul_f32 v[20:21], v[0:1], v[94:95] op_sel_hi:[0,1]
	v_pk_mul_f32 v[22:23], v[0:1], v[90:91] op_sel_hi:[0,1]
	v_pk_mul_f32 v[20:21], v[26:27], v[20:21]
	v_pk_mul_f32 v[22:23], v[28:29], v[22:23]
	v_cvt_pk_bf16_f32 v20, v20, v21
	v_cvt_pk_bf16_f32 v21, v22, v23
	ds_write_b128 v248, v[18:21] offset:4672
	v_pk_mul_f32 v[18:19], v[0:1], v[116:117] op_sel_hi:[0,1]
	v_pk_mul_f32 v[20:21], v[0:1], v[112:113] op_sel_hi:[0,1]
	v_pk_mul_f32 v[18:19], v[34:35], v[18:19]
	v_pk_mul_f32 v[20:21], v[36:37], v[20:21]
	v_cvt_pk_bf16_f32 v18, v18, v19
	v_cvt_pk_bf16_f32 v19, v20, v21
	v_pk_mul_f32 v[20:21], v[0:1], v[110:111] op_sel_hi:[0,1]
	v_pk_mul_f32 v[22:23], v[0:1], v[106:107] op_sel_hi:[0,1]
	v_pk_mul_f32 v[20:21], v[38:39], v[20:21]
	v_pk_mul_f32 v[22:23], v[40:41], v[22:23]
	v_cvt_pk_bf16_f32 v20, v20, v21
	v_cvt_pk_bf16_f32 v21, v22, v23
	ds_write_b128 v248, v[18:21] offset:4736
	v_mov_b32_e32 v18, v58
	v_mov_b32_e32 v19, v62
	v_mov_b32_e32 v62, v59
	v_pk_mul_f32 v[18:19], v[0:1], v[18:19] op_sel_hi:[0,1]
	v_pk_mul_f32 v[20:21], v[0:1], v[62:63] op_sel_hi:[0,1]
	v_pk_mul_f32 v[18:19], v[46:47], v[18:19]
	v_pk_mul_f32 v[20:21], v[48:49], v[20:21]
	v_cvt_pk_bf16_f32 v18, v18, v19
	v_cvt_pk_bf16_f32 v19, v20, v21
	v_mov_b32_e32 v20, v60
	v_mov_b32_e32 v21, v64
	v_mov_b32_e32 v64, v61
	v_pk_mul_f32 v[20:21], v[0:1], v[20:21] op_sel_hi:[0,1]
	v_pk_mul_f32 v[22:23], v[0:1], v[64:65] op_sel_hi:[0,1]
	v_pk_mul_f32 v[20:21], v[42:43], v[20:21]
	v_pk_mul_f32 v[22:23], v[44:45], v[22:23]
	v_cvt_pk_bf16_f32 v20, v20, v21
	v_cvt_pk_bf16_f32 v21, v22, v23
	v_add_u32_e32 v0, v235, v237
	ds_write_b128 v248, v[18:21] offset:4800
	s_waitcnt vmcnt(3)
; #define LAS __attribute__((address_space(3)))
; __device__ __forceinline__ f32x4 mma16(bf16x8 a, bf16x8 b, f32x4 c) { return __builtin_amdgcn_mfma_f32_16x16x32_bf16(a, b, c, 0, 0, 0); }
; __device__ __forceinline__ void attn_phase(LAS unsigned char* lds, const bf16_t* proj, bf16_t* oa, const float* lamp, const float* subg, const float* relb, const float* qg, int wg, int tid) {
;     ...
;         for (int i = 0; i < 2; ++i) { const int id = tid + 512 * i, s = id >> 9, row = (id >> 4) & 31, ch = id & 15;
;             *(LAS u32x4*)(Kb + (s * 32 + row) * KP + ch * 8) = *(const u32x4*)(ksrc + (size_t)row * DIFF_IN + s * 128 + ch * 8); }
; #pragma unroll
;         for (int i = 0; i < 2; ++i) { const int id = tid + 512 * i, row = id >> 5, ch = id & 31;
;             *(LAS u32x4*)(Vb + row * VP + ch * 8) = *(const u32x4*)(vsrc + (size_t)row * DIFF_IN + ch * 8); }
;         __syncthreads();
;         float l0 = 0.f, l1 = 0.f;
;         f32x4 o[2][16];
; #pragma unroll
;         for (int s = 0; s < 2; ++s)
; #pragma unroll
;             for (int vt = 0; vt < 16; ++vt) o[s][vt] = (f32x4){0.f, 0.f, 0.f, 0.f};
;     ...
;             if (k0 <= qw0 + 15) {
;                 const LAS bf16_t* Kc = Kb + cur * KB_BUF; const LAS bf16_t* Vc = Vb + cur * VB_BUF;
;                 const bool far = (qw0 - (k0 + 31)) >= 128;
;                 f32x4 st[2][2];
;                 int qoff = (fr * KP + 8 * fq); asm volatile("" : "+v"(qoff));
; #pragma unroll
;                 for (int s = 0; s < 2; ++s) { const float ini = far ? (s ? c31b : c31a) : 0.f;
;                     st[s][0] = (f32x4){ini, ini, ini, ini}; st[s][1] = st[s][0];
; #pragma unroll
;                     for (int ks = 0; ks < 4; ++ks) { const bf16x8 qfr = *(const LAS bf16x8*)(Qw + s * 16 * KP + qoff + 32 * ks);
; #pragma unroll
;                         for (int T = 0; T < 2; ++T) st[s][T] = mma16(frag_rowk(Kc + s * 32 * KP, KP, 16 * T, 32 * ks, fr, fq), qfr, st[s][T]); } }
	ds_write_b128 v249, v[50:53]
	s_waitcnt vmcnt(2)
	ds_write_b128 v250, v[66:69]
	s_waitcnt vmcnt(1)
	ds_write_b128 v0, v[70:73] offset:36864
	v_add_u32_e32 v0, v235, v238
	v_mov_b32_e32 v20, v1
	v_mov_b32_e32 v21, v1
	s_waitcnt vmcnt(0)
	ds_write_b128 v0, v[74:77] offset:36864
	v_mov_b32_e32 v0, v1
	v_mov_b32_e32 v18, v1
	v_mov_b32_e32 v19, v1
	v_mov_b64_e32 v[24:25], v[20:21]
	v_mov_b64_e32 v[32:33], v[20:21]
	v_mov_b64_e32 v[44:45], v[20:21]
	v_mov_b64_e32 v[52:53], v[20:21]
	v_mov_b64_e32 v[60:61], v[20:21]
	v_mov_b64_e32 v[68:69], v[20:21]
	v_mov_b64_e32 v[76:77], v[20:21]
	v_mov_b64_e32 v[84:85], v[20:21]
	v_mov_b64_e32 v[92:93], v[20:21]
	v_mov_b64_e32 v[100:101], v[20:21]
	v_mov_b64_e32 v[108:109], v[20:21]
	v_mov_b64_e32 v[116:117], v[20:21]
	v_mov_b64_e32 v[124:125], v[20:21]
	v_mov_b64_e32 v[132:133], v[20:21]
	v_mov_b64_e32 v[140:141], v[20:21]
	v_mov_b64_e32 v[28:29], v[20:21]
	v_mov_b64_e32 v[36:37], v[20:21]
	v_mov_b64_e32 v[40:41], v[20:21]
	v_mov_b64_e32 v[48:49], v[20:21]
	v_mov_b64_e32 v[56:57], v[20:21]
	v_mov_b64_e32 v[64:65], v[20:21]
	v_mov_b64_e32 v[72:73], v[20:21]
	v_mov_b64_e32 v[80:81], v[20:21]
	v_mov_b64_e32 v[88:89], v[20:21]
	v_mov_b64_e32 v[96:97], v[20:21]
	v_mov_b64_e32 v[104:105], v[20:21]
	v_mov_b64_e32 v[112:113], v[20:21]
	v_mov_b64_e32 v[120:121], v[20:21]
	v_mov_b64_e32 v[128:129], v[20:21]
	v_mov_b64_e32 v[136:137], v[20:21]
	v_mov_b64_e32 v[144:145], v[20:21]
	v_mov_b64_e32 v[22:23], v[18:19]
	v_mov_b64_e32 v[30:31], v[18:19]
	v_mov_b64_e32 v[42:43], v[18:19]
	v_mov_b64_e32 v[50:51], v[18:19]
	v_mov_b64_e32 v[58:59], v[18:19]
	v_mov_b64_e32 v[66:67], v[18:19]
	v_mov_b64_e32 v[74:75], v[18:19]
	v_mov_b64_e32 v[82:83], v[18:19]
	v_mov_b64_e32 v[90:91], v[18:19]
	v_mov_b64_e32 v[98:99], v[18:19]
	v_mov_b64_e32 v[106:107], v[18:19]
	v_mov_b64_e32 v[114:115], v[18:19]
	v_mov_b64_e32 v[122:123], v[18:19]
	v_mov_b64_e32 v[130:131], v[18:19]
	v_mov_b64_e32 v[138:139], v[18:19]
	v_mov_b64_e32 v[26:27], v[18:19]
	v_mov_b64_e32 v[34:35], v[18:19]
	v_mov_b64_e32 v[38:39], v[18:19]
	v_mov_b64_e32 v[46:47], v[18:19]
	v_mov_b64_e32 v[54:55], v[18:19]
	v_mov_b64_e32 v[62:63], v[18:19]
	v_mov_b64_e32 v[70:71], v[18:19]
	v_mov_b64_e32 v[78:79], v[18:19]
	v_mov_b64_e32 v[86:87], v[18:19]
	v_mov_b64_e32 v[94:95], v[18:19]
	v_mov_b64_e32 v[102:103], v[18:19]
	v_mov_b64_e32 v[110:111], v[18:19]
	v_mov_b64_e32 v[118:119], v[18:19]
	v_mov_b64_e32 v[126:127], v[18:19]
	v_mov_b64_e32 v[134:135], v[18:19]
	v_mov_b64_e32 v[142:143], v[18:19]
	v_mov_b64_e32 v[218:219], v[0:1]
	s_cmpk_gt_i32 s36, 0x7f
	s_cselect_b64 vcc, -1, 0
	v_lshl_add_u32 v0, v236, 1, s44
	ds_read_b128 v[2:5], v0
	ds_read_b128 v[6:9], v0 offset:64
	ds_read_b128 v[10:13], v0 offset:128
	ds_read_b128 v[14:17], v0 offset:192
	v_cndmask_b32_e32 v146, 0, v243, vcc
	v_mov_b32_e32 v147, v146
	v_mov_b32_e32 v148, v146
	v_mov_b32_e32 v149, v146
	v_mov_b32_e32 v150, v146
	v_mov_b32_e32 v151, v146
	v_mov_b32_e32 v152, v146
	v_mov_b32_e32 v153, v146
	v_cndmask_b32_e32 v154, 0, v244, vcc
	v_mov_b32_e32 v155, v154
	v_mov_b32_e32 v156, v154
	v_mov_b32_e32 v157, v154
	v_mov_b32_e32 v158, v154
	v_mov_b32_e32 v159, v154
	v_mov_b32_e32 v160, v154
	v_mov_b32_e32 v161, v154
	s_waitcnt lgkmcnt(0)
	s_barrier
	s_branch .LBB0_595

; #define LAS __attribute__((address_space(3)))
; __device__ __forceinline__ f32x4 mma16(bf16x8 a, bf16x8 b, f32x4 c) { return __builtin_amdgcn_mfma_f32_16x16x32_bf16(a, b, c, 0, 0, 0); }
; __device__ __forceinline__ void attn_phase(LAS unsigned char* lds, const bf16_t* proj, bf16_t* oa, const float* lamp, const float* subg, const float* relb, const float* qg, int wg, int tid) {
;     ...
;             if (k0 <= qw0 + 15) {
;                 const LAS bf16_t* Kc = Kb + cur * KB_BUF; const LAS bf16_t* Vc = Vb + cur * VB_BUF;
;                 const bool far = (qw0 - (k0 + 31)) >= 128;
;                 f32x4 st[2][2];
;                 int qoff = (fr * KP + 8 * fq); asm volatile("" : "+v"(qoff));
; #pragma unroll
;                 for (int s = 0; s < 2; ++s) { const float ini = far ? (s ? c31b : c31a) : 0.f;
;                     st[s][0] = (f32x4){ini, ini, ini, ini}; st[s][1] = st[s][0];
; #pragma unroll
;                     for (int ks = 0; ks < 4; ++ks) { const bf16x8 qfr = *(const LAS bf16x8*)(Qw + s * 16 * KP + qoff + 32 * ks);
; #pragma unroll
;                         for (int T = 0; T < 2; ++T) st[s][T] = mma16(frag_rowk(Kc + s * 32 * KP, KP, 16 * T, 32 * ks, fr, fq), qfr, st[s][T]); } }
.Lat_compute:
	s_mul_i32 s30, s46, 0x4800
	v_add_u32_e32 v0, s30, v245
	ds_read_b128 v[162:165], v0
	ds_read_b128 v[220:223], v0 offset:4608
	ds_read_b128 v[224:227], v0 offset:64
	ds_read_b128 v[228:231], v0 offset:4672
	s_cmpk_gt_i32 s36, 0x7f
	s_cselect_b64 vcc, -1, 0
	s_waitcnt lgkmcnt(2)
	v_mfma_f32_16x16x32_bf16 v[146:149], v[162:165], v[2:5], v[146:149]
	v_mfma_f32_16x16x32_bf16 v[150:153], v[220:223], v[2:5], v[150:153]
	v_lshl_add_u32 v0, v236, 1, s44
	ds_read_b128 v[2:5], v0 offset:4608
	v_add_u32_e32 v0, s30, v245
	ds_read_b128 v[162:165], v0 offset:128
	ds_read_b128 v[220:223], v0 offset:4736
	s_waitcnt lgkmcnt(3)
	v_mfma_f32_16x16x32_bf16 v[146:149], v[224:227], v[6:9], v[146:149]
	v_mfma_f32_16x16x32_bf16 v[150:153], v[228:231], v[6:9], v[150:153]
	v_lshl_add_u32 v0, v236, 1, s44
	ds_read_b128 v[6:9], v0 offset:4672
	v_add_u32_e32 v0, s30, v245
	ds_read_b128 v[224:227], v0 offset:192
	ds_read_b128 v[228:231], v0 offset:4800
	s_waitcnt lgkmcnt(3)
	v_mfma_f32_16x16x32_bf16 v[146:149], v[162:165], v[10:13], v[146:149]
	v_mfma_f32_16x16x32_bf16 v[150:153], v[220:223], v[10:13], v[150:153]
	v_lshl_add_u32 v0, v236, 1, s44
	ds_read_b128 v[10:13], v0 offset:4736
	v_add_u32_e32 v0, s30, v245
	ds_read_b128 v[162:165], v0 offset:9216
	ds_read_b128 v[220:223], v0 offset:13824
	s_waitcnt lgkmcnt(3)
	v_mfma_f32_16x16x32_bf16 v[146:149], v[224:227], v[14:17], v[146:149]
	v_mfma_f32_16x16x32_bf16 v[150:153], v[228:231], v[14:17], v[150:153]
	v_lshl_add_u32 v0, v236, 1, s44
	ds_read_b128 v[14:17], v0 offset:4800
	v_add_u32_e32 v0, s30, v245
	ds_read_b128 v[224:227], v0 offset:9280
	ds_read_b128 v[228:231], v0 offset:13888
	s_waitcnt lgkmcnt(3)
	v_mfma_f32_16x16x32_bf16 v[158:161], v[162:165], v[2:5], v[158:161]
	v_mfma_f32_16x16x32_bf16 v[154:157], v[220:223], v[2:5], v[154:157]
	ds_read_b128 v[162:165], v0 offset:9344
	ds_read_b128 v[220:223], v0 offset:13952
	s_waitcnt lgkmcnt(2)
	v_mfma_f32_16x16x32_bf16 v[158:161], v[224:227], v[6:9], v[158:161]
	v_mfma_f32_16x16x32_bf16 v[154:157], v[228:231], v[6:9], v[154:157]
	ds_read_b128 v[224:227], v0 offset:9408
	ds_read_b128 v[228:231], v0 offset:14016
	s_waitcnt lgkmcnt(2)
	v_mfma_f32_16x16x32_bf16 v[158:161], v[162:165], v[10:13], v[158:161]
	v_mfma_f32_16x16x32_bf16 v[154:157], v[220:223], v[10:13], v[154:157]
	s_waitcnt lgkmcnt(0)
	v_mfma_f32_16x16x32_bf16 v[158:161], v[224:227], v[14:17], v[158:161]
	v_mfma_f32_16x16x32_bf16 v[154:157], v[228:231], v[14:17], v[154:157]
	s_and_b64 s[98:99], s[20:21], exec
	s_cbranch_scc0 .Lat_noload
	v_lshl_add_u64 v[2:3], v[212:213], 0, s[72:73]
	v_lshl_add_u64 v[6:7], v[210:211], 0, s[72:73]
	v_lshl_add_u64 v[10:11], v[214:215], 0, s[72:73]
	v_lshl_add_u64 v[14:15], v[216:217], 0, s[72:73]
	global_load_dwordx4 v[2:5], v[2:3], off
	s_nop 0
	global_load_dwordx4 v[6:9], v[6:7], off
	s_nop 0
	global_load_dwordx4 v[10:13], v[10:11], off
	s_nop 0
	global_load_dwordx4 v[14:17], v[14:15], off

; #define LAS __attribute__((address_space(3)))
; __device__ __forceinline__ void attn_phase(LAS unsigned char* lds, const bf16_t* proj, bf16_t* oa, const float* lamp, const float* subg, const float* relb, const float* qg, int wg, int tid) {
;     ...
;             if (k0 <= qw0 + 15) {
;                 const LAS bf16_t* Kc = Kb + cur * KB_BUF; const LAS bf16_t* Vc = Vb + cur * VB_BUF;
;                 const bool far = (qw0 - (k0 + 31)) >= 128;
;                 f32x4 st[2][2];
;                 int qoff = (fr * KP + 8 * fq); asm volatile("" : "+v"(qoff));
; #pragma unroll
;                 for (int s = 0; s < 2; ++s) { const float ini = far ? (s ? c31b : c31a) : 0.f;
;                     st[s][0] = (f32x4){ini, ini, ini, ini}; st[s][1] = st[s][0];
; #pragma unroll
;                     for (int ks = 0; ks < 4; ++ks) { const bf16x8 qfr = *(const LAS bf16x8*)(Qw + s * 16 * KP + qoff + 32 * ks);
;     ...
;             if (more) {
;                 LAS bf16_t* Kn = Kb + (cur ^ 1) * KB_BUF; LAS bf16_t* Vn = Vb + (cur ^ 1) * VB_BUF;
; #pragma unroll
;                 for (int i = 0; i < 2; ++i) { const int id = tid + 512 * i, s = id >> 9, row = (id >> 4) & 31, ch = id & 15; *(LAS u32x4*)(Kn + (s * 32 + row) * KP + ch * 8) = kr[i]; }
; #pragma unroll
;                 for (int i = 0; i < 2; ++i) { const int id = tid + 512 * i, row = id >> 5, ch = id & 31; *(LAS u32x4*)(Vn + row * VP + ch * 8) = vr[i]; }
;             }
.LBB0_634:
	s_xor_b32 s20, s46, 1
	s_mul_i32 s21, s20, 0x4800
	v_add_u32_e32 v0, s21, v234
	v_add_u32_e32 v146, v0, v239
	v_add_u32_e32 v0, v0, v240
	s_mulk_i32 s20, 0x4400
	s_waitcnt vmcnt(3)
	ds_write_b128 v146, v[2:5]
	s_waitcnt vmcnt(2)
	ds_write_b128 v0, v[6:9]
	v_add_u32_e32 v0, s20, v235
	v_add_u32_e32 v146, v0, v237
	v_add_u32_e32 v0, v0, v238
	s_waitcnt vmcnt(1)
	ds_write_b128 v146, v[10:13] offset:36864
	s_waitcnt vmcnt(0)
	ds_write_b128 v0, v[14:17] offset:36864
	s_sub_i32 s30, s36, 32
	s_cmpk_gt_i32 s30, 0x7f
	s_cselect_b64 vcc, -1, 0
	v_lshl_add_u32 v0, v236, 1, s44
	ds_read_b128 v[2:5], v0
	ds_read_b128 v[6:9], v0 offset:64
	ds_read_b128 v[10:13], v0 offset:128
	ds_read_b128 v[14:17], v0 offset:192
	v_cndmask_b32_e32 v146, 0, v243, vcc
	v_mov_b32_e32 v147, v146
	v_mov_b32_e32 v148, v146
	v_mov_b32_e32 v149, v146
	v_mov_b32_e32 v150, v146
	v_mov_b32_e32 v151, v146
	v_mov_b32_e32 v152, v146
	v_mov_b32_e32 v153, v146
	v_cndmask_b32_e32 v154, 0, v244, vcc
	v_mov_b32_e32 v155, v154
	v_mov_b32_e32 v156, v154
	v_mov_b32_e32 v157, v154
	v_mov_b32_e32 v158, v154
	v_mov_b32_e32 v159, v154
	v_mov_b32_e32 v160, v154
	v_mov_b32_e32 v161, v154
	s_branch .LBB0_594
